# LRU unit prologue: 4 block-weight loads issued together; down-proj epilogue: gate/g_next/scale_next vectors loaded in one batch instead of four serialized stages
# speedup vs baseline: 1.0066x; 1.0047x over previous
.LBB0_249:
	s_mov_b64 s[4:5], s[26:27]
	s_or_b32 s19, s54, s49
	s_add_u32 s20, s4, 0xb100000
	s_mov_b64 s[58:59], s[26:27]
	s_mov_b32 s4, 25
	s_addc_u32 s21, s5, 0
	s_ashr_i32 s5, s4, 31
	s_lshl_b64 s[4:5], s[4:5], 3
	s_add_u32 s4, s0, s4
	s_addc_u32 s5, s1, s5
	s_load_dwordx2 s[22:23], s[4:5], 0x0
	s_mov_b32 s4, 26
	s_ashr_i32 s5, s4, 31
	s_lshl_b64 s[4:5], s[4:5], 3
	s_add_u32 s4, s0, s4
	s_addc_u32 s5, s1, s5
	s_load_dwordx2 s[28:29], s[4:5], 0x0
	s_mov_b32 s4, 28
	s_ashr_i32 s5, s4, 31
	s_lshl_b64 s[4:5], s[4:5], 3
	s_add_u32 s4, s0, s4
	s_addc_u32 s5, s1, s5
	s_load_dwordx2 s[16:17], s[4:5], 0x0
	s_mov_b32 s4, 30
	s_ashr_i32 s5, s4, 31
	s_lshl_b64 s[4:5], s[4:5], 3
	s_add_u32 s4, s0, s4
	s_addc_u32 s5, s1, s5
	s_load_dwordx2 s[38:39], s[4:5], 0x0
	s_mov_b32 s4, 31
	s_ashr_i32 s5, s4, 31
	s_lshl_b64 s[4:5], s[4:5], 3
	s_add_u32 s4, s0, s4
	s_addc_u32 s5, s1, s5
	s_load_dwordx2 s[40:41], s[4:5], 0x0
	s_mov_b32 s4, 7
	s_mov_b32 s4, 8
	s_mov_b64 s[12:13], s[30:31]
	s_mov_b64 s[14:15], s[30:31]
	s_mov_b64 s[34:35], s[26:27]
	s_mov_b64 s[4:5], s[26:27]
	v_mov_b32_e32 v92, v179
	s_lshl_b32 s61, s19, 13
	v_readfirstlane_b32 s18, v92
	s_ashr_i32 s57, s18, 8
	s_lshl_b32 s56, s57, 16
	s_lshl_b32 s60, s57, 1
	s_add_i32 s56, s56, 0
	s_add_i32 s60, s60, s42
	v_lshlrev_b32_e32 v1, 3, v92
	s_add_u32 s58, s58, s61
	v_and_b32_e32 v38, 56, v1
	s_addc_u32 s59, s59, 0
	v_lshlrev_b32_e32 v36, 1, v38
	v_mov_b32_e32 v37, v0
	v_lshl_add_u64 v[2:3], s[58:59], 0, v[36:37]
	s_ashr_i32 s61, s60, 31
	s_waitcnt vmcnt(4)
	v_lshl_add_u64 v[6:7], v[2:3], 0, s[96:97]
	v_bfe_u32 v93, v92, 3, 5
	s_lshl_b64 s[58:59], s[60:61], 17
	v_lshl_add_u64 v[8:9], v[6:7], 0, s[58:59]
	v_lshlrev_b32_e32 v10, 7, v93
	v_mov_b32_e32 v11, v0
	s_waitcnt lgkmcnt(0)
	s_barrier
	v_lshl_add_u64 v[2:3], v[8:9], 0, v[10:11]
	global_load_dwordx4 v[2:5], v[2:3], off
	v_mul_u32_u24_e32 v1, 0x48, v93
	v_add_lshl_u32 v1, v1, v38, 1
	v_or_b32_e32 v95, 32, v93
	v_add_u32_e32 v94, s56, v1
	s_waitcnt vmcnt(4)
	v_lshlrev_b32_e32 v12, 7, v95
	v_mov_b32_e32 v13, v0
	s_or_b32 s58, s60, 1
	s_ashr_i32 s59, s58, 31
	v_add_u32_e32 v1, 0x1200, v1
	s_lshl_b64 s[58:59], s[58:59], 17
	v_add_u32_e32 v96, s56, v1
	v_lshl_add_u64 v[6:7], v[6:7], 0, s[58:59]
	s_lshl_b32 s62, s19, 6
	s_lshl_b32 s19, s57, 10
	s_add_i32 s19, s19, s43
	v_and_b32_e32 v39, 15, v92
	s_add_i32 s19, s19, s62
	s_cmpk_lt_u32 s18, 0x100
	v_mov_b32_e32 v1, v0
	v_lshl_add_u64 v[148:149], v[8:9], 0, v[12:13]
	global_load_dwordx4 v[148:151], v[148:149], off
	v_lshl_add_u64 v[152:153], v[6:7], 0, v[10:11]
	global_load_dwordx4 v[152:155], v[152:153], off
	v_lshl_add_u64 v[156:157], v[6:7], 0, v[12:13]
	global_load_dwordx4 v[156:159], v[156:157], off
	s_waitcnt vmcnt(3)
	ds_write_b128 v94, v[2:5] offset:9216
	s_waitcnt vmcnt(2)
	ds_write_b128 v96, v[148:151] offset:9216
	s_waitcnt vmcnt(1)
	ds_write_b128 v94, v[152:155] offset:18432
	s_waitcnt vmcnt(0)
	ds_write_b128 v96, v[156:159] offset:18432
	v_or_b32_e32 v2, s19, v39
	v_ashrrev_i32_e32 v3, 31, v2
	v_lshlrev_b64 v[2:3], 2, v[2:3]
	s_waitcnt lgkmcnt(0)
	v_lshl_add_u64 v[4:5], s[16:17], 0, v[2:3]
	v_lshl_add_u64 v[6:7], s[38:39], 0, v[2:3]
	v_lshl_add_u64 v[2:3], s[40:41], 0, v[2:3]
	global_load_dword v97, v[4:5], off
	global_load_dword v98, v[6:7], off
	global_load_dword v43, v[2:3], off
	global_load_dword v99, v[4:5], off offset:64
	global_load_dword v100, v[6:7], off offset:64
	global_load_dword v42, v[2:3], off offset:64
	global_load_dword v101, v[4:5], off offset:128
	global_load_dword v102, v[6:7], off offset:128
	global_load_dword v40, v[2:3], off offset:128
	global_load_dword v103, v[4:5], off offset:192
	global_load_dword v104, v[6:7], off offset:192
	global_load_dword v41, v[2:3], off offset:192
	s_cselect_b64 s[16:17], -1, 0
	s_and_b64 s[38:39], s[16:17], exec
	s_cselect_b32 s19, -2, 0xbe
	v_mov_b32_e32 v2, v0
	v_mov_b32_e32 v3, v0
	v_add_u32_e32 v12, s19, v93
	v_mov_b64_e32 v[6:7], v[2:3]
	v_cmp_gt_u32_e32 vcc, s33, v12
	v_mov_b64_e32 v[4:5], v[0:1]
	s_and_saveexec_b64 s[38:39], vcc
	s_cbranch_execz .LBB0_251
	v_or_b32_e32 v4, s50, v12
	v_mov_b32_e32 v5, v0
	v_lshlrev_b64 v[4:5], 12, v[4:5]
	v_lshl_add_u64 v[4:5], s[20:21], 0, v[4:5]
	s_lshl_b32 s40, s62, 1
	s_mov_b32 s41, s63
	v_lshl_add_u64 v[4:5], v[4:5], 0, s[40:41]
	v_lshl_add_u64 v[4:5], v[4:5], 0, v[36:37]
	global_load_dwordx4 v[4:7], v[4:5], off offset:2048

.LBB0_278:
	s_and_b64 vcc, exec, s[4:5]
	s_cbranch_vccz .LBB0_245
	s_mov_b64 s[12:13], s[26:27]
	s_mov_b64 s[50:51], s[26:27]
	s_mov_b32 s4, 25
	s_ashr_i32 s5, s4, 31
	s_and_b32 s19, s48, 15
	s_lshl_b64 s[4:5], s[4:5], 3
	s_add_u32 s4, s0, s4
	s_addc_u32 s5, s1, s5
	s_load_dwordx2 s[14:15], s[4:5], 0x0
	s_mov_b32 s4, 26
	s_ashr_i32 s5, s4, 31
	s_lshl_b64 s[4:5], s[4:5], 3
	s_add_u32 s4, s0, s4
	s_addc_u32 s5, s1, s5
	s_load_dwordx2 s[16:17], s[4:5], 0x0
	s_mov_b32 s4, 28
	s_ashr_i32 s5, s4, 31
	s_lshl_b64 s[4:5], s[4:5], 3
	s_add_u32 s4, s0, s4
	s_addc_u32 s5, s1, s5
	s_load_dwordx2 s[10:11], s[4:5], 0x0
	s_mov_b32 s4, 30
	s_ashr_i32 s5, s4, 31
	s_lshl_b64 s[4:5], s[4:5], 3
	s_add_u32 s4, s0, s4
	s_addc_u32 s5, s1, s5
	s_load_dwordx2 s[34:35], s[4:5], 0x0
	s_mov_b32 s4, 31
	s_ashr_i32 s5, s4, 31
	s_lshl_b64 s[4:5], s[4:5], 3
	s_add_u32 s4, s0, s4
	s_addc_u32 s5, s1, s5
	s_load_dwordx2 s[38:39], s[4:5], 0x0
	s_mov_b32 s28, 7
	s_mov_b32 s22, 8
	s_mov_b64 s[4:5], s[30:31]
	s_mov_b64 s[4:5], s[30:31]
	s_mov_b64 s[20:21], s[26:27]
	s_mov_b64 s[4:5], s[26:27]
	v_mov_b32_e32 v92, v179
	v_mov_b32_e32 v37, v0
	v_readfirstlane_b32 s18, v92
	s_ashr_i32 s23, s18, 8
	s_lshl_b32 s29, s23, 16
	s_add_i32 s40, s29, 0
	s_lshl_b32 s29, s23, 1
	s_add_i32 s52, s29, s42
	s_lshl_b32 s29, s19, 13
	v_lshlrev_b32_e32 v1, 3, v92
	s_add_u32 s50, s50, s29
	v_and_b32_e32 v40, 56, v1
	s_addc_u32 s51, s51, 0
	v_lshlrev_b32_e32 v36, 1, v40
	v_lshl_add_u64 v[2:3], s[50:51], 0, v[36:37]
	s_ashr_i32 s53, s52, 31
	s_waitcnt vmcnt(4)
	v_lshl_add_u64 v[6:7], v[2:3], 0, s[56:57]
	v_bfe_u32 v93, v92, 3, 5
	s_lshl_b64 s[50:51], s[52:53], 17
	v_lshl_add_u64 v[8:9], v[6:7], 0, s[50:51]
	v_lshlrev_b32_e32 v10, 7, v93
	v_mov_b32_e32 v11, v0
	s_waitcnt lgkmcnt(0)
	s_barrier
	v_lshl_add_u64 v[2:3], v[8:9], 0, v[10:11]
	global_load_dwordx4 v[2:5], v[2:3], off
	v_mul_u32_u24_e32 v1, 0x48, v93
	v_add_lshl_u32 v1, v1, v40, 1
	v_or_b32_e32 v95, 32, v93
	v_add_u32_e32 v94, s40, v1
	s_waitcnt vmcnt(4)
	v_lshlrev_b32_e32 v12, 7, v95
	v_mov_b32_e32 v13, v0
	s_or_b32 s50, s52, 1
	s_ashr_i32 s51, s50, 31
	v_add_u32_e32 v1, 0x1200, v1
	s_lshl_b64 s[50:51], s[50:51], 17
	v_add_u32_e32 v96, s40, v1
	v_lshl_add_u64 v[6:7], v[6:7], 0, s[50:51]
	s_lshl_b32 s62, s19, 6
	s_lshl_b32 s19, s23, 10
	s_add_i32 s19, s19, s43
	v_and_b32_e32 v41, 15, v92
	s_or_b32 s19, s19, s62
	v_mov_b32_e32 v1, 63
	v_lshl_add_u64 v[148:149], v[8:9], 0, v[12:13]
	global_load_dwordx4 v[148:151], v[148:149], off
	v_lshl_add_u64 v[152:153], v[6:7], 0, v[10:11]
	global_load_dwordx4 v[152:155], v[152:153], off
	v_lshl_add_u64 v[156:157], v[6:7], 0, v[12:13]
	global_load_dwordx4 v[156:159], v[156:157], off
	s_waitcnt vmcnt(3)
	ds_write_b128 v94, v[2:5] offset:9216
	s_waitcnt vmcnt(2)
	ds_write_b128 v96, v[148:151] offset:9216
	s_waitcnt vmcnt(1)
	ds_write_b128 v94, v[152:155] offset:18432
	s_waitcnt vmcnt(0)
	ds_write_b128 v96, v[156:159] offset:18432
	v_or_b32_e32 v2, s19, v41
	v_ashrrev_i32_e32 v3, 31, v2
	v_lshlrev_b64 v[2:3], 2, v[2:3]
	s_waitcnt lgkmcnt(0)
	v_lshl_add_u64 v[4:5], s[10:11], 0, v[2:3]
	v_lshl_add_u64 v[6:7], s[34:35], 0, v[2:3]
	v_lshl_add_u64 v[2:3], s[38:39], 0, v[2:3]
	global_load_dword v97, v[4:5], off
	global_load_dword v98, v[6:7], off
	global_load_dword v45, v[2:3], off
	global_load_dword v99, v[4:5], off offset:64
	global_load_dword v100, v[6:7], off offset:64
	global_load_dword v44, v[2:3], off offset:64
	global_load_dword v101, v[4:5], off offset:128
	global_load_dword v102, v[6:7], off offset:128
	global_load_dword v42, v[2:3], off offset:128
	global_load_dword v103, v[4:5], off offset:192
	global_load_dword v104, v[6:7], off offset:192
	global_load_dword v43, v[2:3], off offset:192
	v_cmp_lt_u32_sdwa s[10:11], v92, v233 src0_sel:BYTE_0 src1_sel:DWORD
	v_cmp_gt_u32_sdwa s[34:35], v92, v1 src0_sel:BYTE_0 src1_sel:DWORD
	v_mov_b64_e32 v[4:5], s[62:63]
	s_and_saveexec_b64 s[38:39], s[34:35]
	s_xor_b64 s[34:35], exec, s[38:39]
	v_mov_b64_e32 v[4:5], s[62:63]
	s_or_saveexec_b64 s[34:35], s[34:35]
	s_ashr_i32 s19, s48, 4
	v_mov_b32_e32 v91, 0
	s_xor_b64 exec, exec, s[34:35]
	s_cbranch_execz .LBB0_283
	s_ashr_i32 s29, s28, 31
	s_lshl_b64 s[28:29], s[28:29], 3
	s_add_u32 s28, s0, s28
	s_addc_u32 s29, s1, s29
	s_ashr_i32 s23, s22, 31
	s_lshl_b64 s[22:23], s[22:23], 3
	s_add_u32 s22, s0, s22
	s_addc_u32 s23, s1, s23
	s_load_dwordx2 s[28:29], s[28:29], 0x0
	s_nop 0
	s_load_dwordx2 s[22:23], s[22:23], 0x0
	s_cmpk_lt_u32 s18, 0x100
	v_readlane_b32 s38, v254, 60
	v_lshlrev_b32_sdwa v1, v236, v92 dst_sel:DWORD dst_unused:UNUSED_PAD src0_sel:DWORD src1_sel:BYTE_0
	v_readlane_b32 s39, v254, 61
	s_waitcnt lgkmcnt(0)
	s_cselect_b32 s29, s29, s23
	s_cselect_b32 s28, s28, s22
	s_lshl_b32 s22, s19, 1
	s_add_i32 s22, s22, s38
	s_ashr_i32 s23, s22, 31
	s_lshl_b64 s[22:23], s[22:23], 12
	s_add_u32 s22, s28, s22
	s_addc_u32 s23, s29, s23
	s_lshl_b32 s28, s62, 2
	s_add_u32 s22, s22, s28
	s_addc_u32 s23, s23, 0
	global_load_dword v91, v1, s[22:23]

.LBB0_1474:
	s_lshl_b32 s8, s62, 8
	s_or_b32 s8, s8, s58
	v_lshl_add_u32 v202, v170, 3, s8
	s_lshl_b64 s[6:7], s[6:7], 2
	s_add_u32 s8, s59, s6
	v_ashrrev_i32_e32 v203, 31, v202
	s_addc_u32 s9, s60, s7
	v_lshlrev_b64 v[146:147], 2, v[202:203]
	v_lshl_add_u64 v[78:79], s[8:9], 0, v[146:147]
	global_load_dwordx4 v[82:85], v[78:79], off
	s_add_u32 s6, s52, s6
	s_addc_u32 s7, s53, s7
	v_cndmask_b32_e64 v74, 0, 1, s[18:19]
	v_lshl_add_u64 v[148:149], s[14:15], 0, v[146:147]
	v_lshl_add_u64 v[150:151], s[6:7], 0, v[146:147]
	v_mov_b32_e32 v204, 0
	v_cmp_ne_u32_e64 s[6:7], 1, v74
	s_andn2_b64 vcc, exec, s[18:19]
	v_mov_b32_e32 v206, 0
	v_mov_b32_e32 v207, 0
	v_mov_b32_e32 v210, 0
	v_mov_b32_e32 v211, 0
	s_mov_b32 s71, 0xb000
	s_mov_b32 s70, 0xd000
	v_mov_b32_e32 v205, 0
	v_mov_b32_e32 v216, 0
	v_mov_b32_e32 v217, 0
	v_mov_b32_e32 v208, 0
	v_mov_b32_e32 v212, 0
	v_mov_b32_e32 v213, 0
	v_mov_b32_e32 v214, 0
	v_mov_b32_e32 v215, 0
	v_mov_b32_e32 v209, 0
	v_mov_b32_e32 v218, 0
	v_mov_b32_e32 v219, 0
	s_load_dwordx2 s[74:75], s[0:1], 0x140
	global_load_dwordx4 v[86:89], v[78:79], off offset:16
	global_load_dwordx4 v[74:77], v[78:79], off offset:512
	global_load_dwordx4 v[78:81], v[78:79], off offset:528
	s_cbranch_vccnz .Ldgs_skip
	global_load_dwordx4 v[162:165], v[150:151], off
	global_load_dwordx4 v[166:169], v[150:151], off offset:16
	global_load_dwordx4 v[172:175], v[150:151], off offset:512
	global_load_dwordx4 v[184:187], v[150:151], off offset:528
	global_load_dwordx4 v[220:223], v[148:149], off
	global_load_dwordx4 v[224:227], v[148:149], off offset:16
	global_load_dwordx4 v[244:247], v[148:149], off offset:512
	global_load_dwordx4 v[148:151], v[148:149], off offset:528
	s_waitcnt vmcnt(0)
	v_pk_add_f32 v[164:165], v[164:165], 1.0 op_sel_hi:[1,0]
	v_pk_add_f32 v[162:163], v[162:163], 1.0 op_sel_hi:[1,0]
	v_pk_mul_f32 v[210:211], v[222:223], v[164:165]
	v_pk_mul_f32 v[206:207], v[220:221], v[162:163]
	v_pk_add_f32 v[168:169], v[168:169], 1.0 op_sel_hi:[1,0]
	v_pk_add_f32 v[166:167], v[166:167], 1.0 op_sel_hi:[1,0]
	v_pk_mul_f32 v[216:217], v[226:227], v[168:169]
	v_pk_mul_f32 v[204:205], v[224:225], v[166:167]
	v_pk_add_f32 v[174:175], v[174:175], 1.0 op_sel_hi:[1,0]
	v_pk_add_f32 v[172:173], v[172:173], 1.0 op_sel_hi:[1,0]
	v_pk_mul_f32 v[214:215], v[246:247], v[174:175]
	v_pk_mul_f32 v[212:213], v[244:245], v[172:173]
	v_pk_add_f32 v[186:187], v[186:187], 1.0 op_sel_hi:[1,0]
	v_pk_add_f32 v[184:185], v[184:185], 1.0 op_sel_hi:[1,0]
	v_pk_mul_f32 v[218:219], v[150:151], v[186:187]
	v_pk_mul_f32 v[208:209], v[148:149], v[184:185]
.Ldgs_skip:
.LBB0_1482:
	s_lshl_b32 s8, s68, 8
	s_add_i32 s8, s8, s57
	v_add_u32_e32 v220, s8, v152
	v_ashrrev_i32_e32 v221, 31, v220
	v_lshlrev_b64 v[148:149], 12, v[220:221]
	v_add_u32_e32 v224, 16, v220
	v_lshl_add_u64 v[148:149], s[10:11], 0, v[148:149]
	v_ashrrev_i32_e32 v225, 31, v224
	v_lshl_add_u64 v[226:227], v[148:149], 0, v[146:147]
	v_lshlrev_b64 v[148:149], 12, v[224:225]
	v_lshl_add_u64 v[148:149], s[10:11], 0, v[148:149]
	v_lshl_add_u64 v[222:223], v[148:149], 0, v[146:147]
	global_load_dwordx4 v[184:187], v[226:227], off offset:16
	global_load_dwordx4 v[172:175], v[226:227], off
	global_load_dwordx4 v[162:165], v[226:227], off offset:528
	global_load_dwordx4 v[166:169], v[226:227], off offset:512
	global_load_dwordx4 v[154:157], v[222:223], off offset:16
	global_load_dwordx4 v[158:161], v[222:223], off
	global_load_dwordx4 v[146:149], v[222:223], off offset:528
	global_load_dwordx4 v[150:153], v[222:223], off offset:512
	s_lshl_b32 s28, s62, 2
	v_cmp_eq_u32_e64 s[8:9], 0, v170
	s_and_b64 vcc, exec, s[6:7]
	s_ashr_i32 s29, s28, 31
	s_waitcnt vmcnt(0)
	v_pk_fma_f32 v[170:171], v[138:139], v[86:87], v[184:185]
	v_pk_fma_f32 v[176:177], v[144:145], v[84:85], v[174:175]
	v_pk_fma_f32 v[174:175], v[142:143], v[82:83], v[172:173]
	v_pk_fma_f32 v[172:173], v[140:141], v[88:89], v[186:187]
	v_pk_fma_f32 v[142:143], v[134:135], v[74:75], v[166:167]
	v_pk_fma_f32 v[138:139], v[130:131], v[78:79], v[162:163]
	global_store_dwordx4 v[226:227], v[174:177], off
	global_store_dwordx4 v[226:227], v[170:173], off offset:16
	s_cbranch_vccnz .LBB0_1521
	v_mul_f32_e32 v130, v175, v175
	v_mul_f32_e32 v131, v177, v177
	v_fmac_f32_e32 v130, v174, v174
	v_fmac_f32_e32 v131, v176, v176
	v_add_f32_e32 v130, v130, v131
	v_mul_f32_e32 v131, v171, v171
	v_mul_f32_e32 v134, v173, v173
	v_fmac_f32_e32 v131, v170, v170
	v_fmac_f32_e32 v134, v172, v172
	v_pk_mul_f32 v[144:145], v[204:205], v[170:171]
	v_add_f32_e32 v131, v131, v134
	v_pk_mul_f32 v[134:135], v[206:207], v[174:175]
	v_pk_mul_f32 v[140:141], v[216:217], v[172:173]
	v_cvt_pk_bf16_f32 v172, v144, v145
	v_pk_fma_f32 v[144:145], v[136:137], v[76:77], v[168:169]
	v_cvt_pk_bf16_f32 v170, v134, v135
	v_mul_f32_e32 v134, v143, v143
	v_mul_f32_e32 v135, v145, v145
	v_cvt_pk_bf16_f32 v173, v140, v141
	v_pk_fma_f32 v[140:141], v[132:133], v[80:81], v[164:165]
	v_fmac_f32_e32 v134, v142, v142
	v_fmac_f32_e32 v135, v144, v144
	v_add_f32_e32 v162, v130, v131
	v_pk_mul_f32 v[130:131], v[210:211], v[176:177]
	v_add_f32_e32 v134, v134, v135
	v_mul_f32_e32 v135, v139, v139
	v_mul_f32_e32 v163, v141, v141
	v_cvt_pk_bf16_f32 v171, v130, v131
	v_lshlrev_b64 v[130:131], 11, v[220:221]
	v_fmac_f32_e32 v135, v138, v138
	v_fmac_f32_e32 v163, v140, v140
	v_lshl_add_u64 v[130:131], s[12:13], 0, v[130:131]
	v_add_f32_e32 v135, v135, v163
	v_lshl_add_u64 v[130:131], v[202:203], 1, v[130:131]
	v_add_f32_e32 v134, v134, v135
	global_store_dwordx4 v[130:131], v[170:173], off
	global_store_dwordx4 v[226:227], v[142:145], off offset:512
	global_store_dwordx4 v[226:227], v[138:141], off offset:528
	v_add_f32_e32 v166, v162, v134
	v_pk_mul_f32 v[134:135], v[214:215], v[144:145]
	v_pk_mul_f32 v[144:145], v[212:213], v[142:143]
	v_pk_mul_f32 v[140:141], v[218:219], v[140:141]
	v_pk_mul_f32 v[162:163], v[208:209], v[138:139]
	v_cvt_pk_bf16_f32 v170, v144, v145
	v_cvt_pk_bf16_f32 v171, v134, v135
	v_cvt_pk_bf16_f32 v172, v162, v163
	v_cvt_pk_bf16_f32 v173, v140, v141
	global_store_dwordx4 v[130:131], v[170:173], off offset:256
	v_mov_b32_e32 v130, v166
	s_nop 1
	v_permlane16_swap_b32_e32 v166, v130
	v_add_f32_e32 v130, v166, v130
	v_mov_b32_e32 v131, v130
	s_nop 1
	v_permlane32_swap_b32_e32 v130, v131
	s_and_saveexec_b64 s[34:35], s[8:9]
	s_cbranch_execz .LBB0_1485
	v_lshlrev_b64 v[134:135], 6, v[220:221]
	v_lshl_add_u64 v[134:135], s[16:17], 0, v[134:135]
	v_lshl_add_u64 v[134:135], s[28:29], 2, v[134:135]
	s_lshl_b32 s62, s56, 2
	v_lshl_add_u64 v[134:135], v[134:135], 0, s[62:63]
	v_add_f32_e32 v130, v130, v131
	global_store_dword v[134:135], v130, off
